# prep: silu(c) table loads batched 8 at a time; weight-transpose tiles split 15 per ada workgroup / 35 per other workgroup
# speedup vs baseline: 1.0578x; 1.0051x over previous
.LBB0_5:
	s_or_b64 exec, exec, s[6:7]
	s_mov_b64 s[26:27], s[94:95]
	s_load_dwordx4 s[8:11], s[26:27], 0x10
	s_load_dwordx4 s[12:15], s[26:27], 0x50
	s_load_dwordx2 s[22:23], s[26:27], 0x60
	s_load_dwordx2 s[6:7], s[26:27], 0xd0
	v_mov_b32_e32 v6, v214
	s_cmpk_gt_i32 s2, 0x13ff
	s_cbranch_scc1 .LBB0_19
	s_waitcnt lgkmcnt(0)
	s_add_u32 s0, s6, 0x2400000
	s_load_dwordx4 s[16:19], s[26:27], 0x88
	s_load_dwordx2 s[24:25], s[26:27], 0xc0
	s_addc_u32 s1, s7, 0
	s_add_u32 s3, s6, 0x1400000
	s_addc_u32 s4, s7, 0
	s_add_u32 s5, s6, 0x1000000
	s_addc_u32 s33, s7, 0
	s_mov_b32 s27, 0
	v_mov_b32_e32 v3, 0
	s_movk_i32 s44, 0x104
	s_mov_b32 s45, s2
	s_mov_b32 s48, s42
	s_movk_i32 s49, 0x1400
	s_cmpk_lg_i32 s42, 0x100
	s_cbranch_scc1 .Lprep_split_done
	s_add_i32 s45, s2, 0xb40
	s_sub_i32 s50, s2, 64
	s_cmp_lt_u32 s2, 64
	s_cselect_b32 s48, 64, 0xc0
	s_movk_i32 s51, 0xb40
	s_cselect_b32 s49, s49, s51
	s_cselect_b32 s45, s45, s50

.LBB0_7:
	s_lshl_b32 s26, s46, 2
	s_and_b32 s36, s26, 0xffffffc0
	s_lshl_b32 s26, s46, 6
	v_mov_b32_e32 v1, v214
	s_ashr_i32 s37, s36, 31
	s_and_b32 s26, s26, 0x3c0
	s_lshl_b64 s[40:41], s[36:37], 2
	v_ashrrev_i32_e32 v7, 4, v1
	v_add_u32_e32 v12, s26, v7
	s_add_u32 s34, s34, s40
	v_lshlrev_b32_e32 v2, 4, v1
	s_addc_u32 s35, s35, s41
	v_and_b32_e32 v2, 0xf0, v2
	v_ashrrev_i32_e32 v8, 31, v12
	v_lshl_add_u64 v[4:5], s[34:35], 0, v[2:3]
	v_mul_lo_u32 v10, s38, v8
	v_mul_lo_u32 v11, s39, v12
	v_mad_u64_u32 v[8:9], s[34:35], s38, v12, 0
	v_add_u32_e32 v12, 32, v12
	v_add3_u32 v9, v9, v10, v11
	v_ashrrev_i32_e32 v13, 31, v12
	v_lshl_add_u64 v[8:9], v[8:9], 2, v[4:5]
	v_mul_lo_u32 v14, s38, v13
	v_mul_lo_u32 v15, s39, v12
	v_mad_u64_u32 v[12:13], s[34:35], s38, v12, 0
	global_load_dwordx4 v[8:11], v[8:9], off
	v_add3_u32 v13, v13, v14, v15
	v_lshl_add_u64 v[4:5], v[12:13], 2, v[4:5]
	global_load_dwordx4 v[12:15], v[4:5], off
	v_ashrrev_i32_e32 v16, 3, v1
	v_mul_lo_u32 v5, v7, s44
	v_lshlrev_b32_e32 v17, 1, v16
	v_lshrrev_b32_e32 v18, 1, v16
	v_and_b32_e32 v7, 15, v16
	v_add3_u32 v19, 0, v2, v5
	v_and_b32_e32 v2, 32, v17
	v_and_b32_e32 v17, 16, v18
	v_lshlrev_b32_e32 v1, 3, v1
	v_or3_b32 v2, v2, v7, v17
	v_and_b32_e32 v1, 56, v1
	v_cndmask_b32_e64 v7, v16, v2, s[30:31]
	v_mul_u32_u24_e32 v18, 0x104, v1
	v_lshlrev_b32_e32 v2, 1, v1
	v_lshlrev_b32_e32 v1, 2, v7
	v_add3_u32 v1, 0, v1, v18
	v_add_u32_e32 v4, s36, v16
	v_add_u32_e32 v20, 0x2080, v19
	v_add_u32_e32 v21, 0x2088, v19
	v_add_u32_e32 v7, 0x400, v1
	v_ashrrev_i32_e32 v5, 31, v4
	v_lshlrev_b64 v[4:5], 11, v[4:5]
	s_lshl_b32 s26, s26, 1
	v_lshl_add_u64 v[4:5], s[28:29], 0, v[4:5]
	s_add_i32 s45, s45, s48
	v_lshl_add_u64 v[4:5], v[4:5], 0, s[26:27]
	s_cmp_ge_i32 s45, s49
	v_lshl_add_u64 v[4:5], v[4:5], 0, v[2:3]
	s_waitcnt vmcnt(1)
	ds_write2_b32 v19, v8, v9 offset1:1
	ds_write2_b32 v19, v10, v11 offset0:2 offset1:3
	s_waitcnt vmcnt(0)
	ds_write2_b32 v20, v12, v13 offset1:1
	ds_write2_b32 v21, v14, v15 offset1:1
	s_waitcnt lgkmcnt(0)
	s_barrier
	ds_read2_b32 v[8:9], v1 offset1:65
	ds_read2_b32 v[10:11], v1 offset0:130 offset1:195
	ds_read2_b32 v[12:13], v7 offset0:4 offset1:69
	ds_read2_b32 v[14:15], v7 offset0:134 offset1:199
	s_waitcnt lgkmcnt(3)
	v_cvt_pk_bf16_f32 v8, v8, v9
	s_waitcnt lgkmcnt(2)
	v_cvt_pk_bf16_f32 v9, v10, v11
	s_waitcnt lgkmcnt(1)
	v_cvt_pk_bf16_f32 v10, v12, v13
	s_waitcnt lgkmcnt(0)
	v_cvt_pk_bf16_f32 v11, v14, v15
	global_store_dwordx4 v[4:5], v[8:11], off
	s_barrier
	s_cbranch_scc1 .LBB0_19

.LBB0_25:
	s_xor_b64 s[6:7], s[16:17], -1
	s_and_saveexec_b64 s[16:17], s[6:7]
	s_cbranch_execz .LBB0_30
	s_mov_b64 s[18:19], 0x1000
	v_mov_b64_e32 v[2:3], v[12:13]
	s_mov_b64 s[22:23], s[10:11]
	v_add_u32_e32 v51, 0x10000, v7
	global_load_dword v16, v[2:3], off
	global_load_dword v17, v[2:3], off offset:2048
	v_lshl_add_u64 v[2:3], v[2:3], 0, s[18:19]
	global_load_dword v18, v[2:3], off
	global_load_dword v19, v[2:3], off offset:2048
	v_lshl_add_u64 v[2:3], v[2:3], 0, s[18:19]
	global_load_dword v20, v[2:3], off
	global_load_dword v21, v[2:3], off offset:2048
	v_lshl_add_u64 v[2:3], v[2:3], 0, s[18:19]
	global_load_dword v22, v[2:3], off
	global_load_dword v23, v[2:3], off offset:2048
	global_load_dword v24, v7, s[22:23]
	global_load_dword v25, v7, s[22:23] offset:2048
	s_add_u32 s22, s22, 0x1000
	s_addc_u32 s23, s23, 0
	global_load_dword v26, v7, s[22:23]
	global_load_dword v27, v7, s[22:23] offset:2048
	s_add_u32 s22, s22, 0x1000
	s_addc_u32 s23, s23, 0
	global_load_dword v28, v7, s[22:23]
	global_load_dword v29, v7, s[22:23] offset:2048
	s_add_u32 s22, s22, 0x1000
	s_addc_u32 s23, s23, 0
	global_load_dword v30, v7, s[22:23]
	global_load_dword v31, v7, s[22:23] offset:2048
	s_waitcnt vmcnt(8)
	v_mul_f32_e32 v43, 0xbfb8aa3b, v16
	v_mul_f32_e32 v44, 0xbfb8aa3b, v17
	v_mul_f32_e32 v45, 0xbfb8aa3b, v18
	v_mul_f32_e32 v46, 0xbfb8aa3b, v19
	v_mul_f32_e32 v47, 0xbfb8aa3b, v20
	v_mul_f32_e32 v48, 0xbfb8aa3b, v21
	v_mul_f32_e32 v49, 0xbfb8aa3b, v22
	v_mul_f32_e32 v50, 0xbfb8aa3b, v23
	v_exp_f32_e32 v43, v43
	v_exp_f32_e32 v44, v44
	v_exp_f32_e32 v45, v45
	v_exp_f32_e32 v46, v46
	v_exp_f32_e32 v47, v47
	v_exp_f32_e32 v48, v48
	v_exp_f32_e32 v49, v49
	v_exp_f32_e32 v50, v50
	v_add_f32_e32 v43, 1.0, v43
	v_add_f32_e32 v44, 1.0, v44
	v_add_f32_e32 v45, 1.0, v45
	v_add_f32_e32 v46, 1.0, v46
	v_add_f32_e32 v47, 1.0, v47
	v_add_f32_e32 v48, 1.0, v48
	v_add_f32_e32 v49, 1.0, v49
	v_add_f32_e32 v50, 1.0, v50
	v_rcp_f32_e32 v43, v43
	v_rcp_f32_e32 v44, v44
	v_rcp_f32_e32 v45, v45
	v_rcp_f32_e32 v46, v46
	v_rcp_f32_e32 v47, v47
	v_rcp_f32_e32 v48, v48
	v_rcp_f32_e32 v49, v49
	v_rcp_f32_e32 v50, v50
	v_mul_f32_e32 v16, v16, v43
	v_mul_f32_e32 v17, v17, v44
	v_mul_f32_e32 v18, v18, v45
	v_mul_f32_e32 v19, v19, v46
	v_mul_f32_e32 v20, v20, v47
	v_mul_f32_e32 v21, v21, v48
	v_mul_f32_e32 v22, v22, v49
	v_mul_f32_e32 v23, v23, v50
	ds_write_b32 v7, v16
	ds_write_b32 v7, v17 offset:2048
	ds_write_b32 v7, v18 offset:4096
	ds_write_b32 v7, v19 offset:6144
	ds_write_b32 v7, v20 offset:8192
	ds_write_b32 v7, v21 offset:10240
	ds_write_b32 v7, v22 offset:12288
	ds_write_b32 v7, v23 offset:14336
	s_add_u32 s22, s22, 0x1000
	s_addc_u32 s23, s23, 0
	global_load_dword v16, v7, s[22:23]
	global_load_dword v17, v7, s[22:23] offset:2048
	s_add_u32 s22, s22, 0x1000
	s_addc_u32 s23, s23, 0
	global_load_dword v18, v7, s[22:23]
	global_load_dword v19, v7, s[22:23] offset:2048
	s_add_u32 s22, s22, 0x1000
	s_addc_u32 s23, s23, 0
	global_load_dword v20, v7, s[22:23]
	global_load_dword v21, v7, s[22:23] offset:2048
	s_add_u32 s22, s22, 0x1000
	s_addc_u32 s23, s23, 0
	global_load_dword v22, v7, s[22:23]
	global_load_dword v23, v7, s[22:23] offset:2048
	s_waitcnt vmcnt(8)
	v_mul_f32_e32 v43, 0xbfb8aa3b, v24
	v_mul_f32_e32 v44, 0xbfb8aa3b, v25
	v_mul_f32_e32 v45, 0xbfb8aa3b, v26
	v_mul_f32_e32 v46, 0xbfb8aa3b, v27
	v_mul_f32_e32 v47, 0xbfb8aa3b, v28
	v_mul_f32_e32 v48, 0xbfb8aa3b, v29
	v_mul_f32_e32 v49, 0xbfb8aa3b, v30
	v_mul_f32_e32 v50, 0xbfb8aa3b, v31
	v_exp_f32_e32 v43, v43
	v_exp_f32_e32 v44, v44
	v_exp_f32_e32 v45, v45
	v_exp_f32_e32 v46, v46
	v_exp_f32_e32 v47, v47
	v_exp_f32_e32 v48, v48
	v_exp_f32_e32 v49, v49
	v_exp_f32_e32 v50, v50
	v_add_f32_e32 v43, 1.0, v43
	v_add_f32_e32 v44, 1.0, v44
	v_add_f32_e32 v45, 1.0, v45
	v_add_f32_e32 v46, 1.0, v46
	v_add_f32_e32 v47, 1.0, v47
	v_add_f32_e32 v48, 1.0, v48
	v_add_f32_e32 v49, 1.0, v49
	v_add_f32_e32 v50, 1.0, v50
	v_rcp_f32_e32 v43, v43
	v_rcp_f32_e32 v44, v44
	v_rcp_f32_e32 v45, v45
	v_rcp_f32_e32 v46, v46
	v_rcp_f32_e32 v47, v47
	v_rcp_f32_e32 v48, v48
	v_rcp_f32_e32 v49, v49
	v_rcp_f32_e32 v50, v50
	v_mul_f32_e32 v24, v24, v43
	v_mul_f32_e32 v25, v25, v44
	v_mul_f32_e32 v26, v26, v45
	v_mul_f32_e32 v27, v27, v46
	v_mul_f32_e32 v28, v28, v47
	v_mul_f32_e32 v29, v29, v48
	v_mul_f32_e32 v30, v30, v49
	v_mul_f32_e32 v31, v31, v50
	ds_write_b32 v7, v24 offset:16384
	ds_write_b32 v7, v25 offset:18432
	ds_write_b32 v7, v26 offset:20480
	ds_write_b32 v7, v27 offset:22528
	ds_write_b32 v7, v28 offset:24576
	ds_write_b32 v7, v29 offset:26624
	ds_write_b32 v7, v30 offset:28672
	ds_write_b32 v7, v31 offset:30720
	s_add_u32 s22, s22, 0x1000
	s_addc_u32 s23, s23, 0
	global_load_dword v24, v7, s[22:23]
	global_load_dword v25, v7, s[22:23] offset:2048
	s_add_u32 s22, s22, 0x1000
	s_addc_u32 s23, s23, 0
	global_load_dword v26, v7, s[22:23]
	global_load_dword v27, v7, s[22:23] offset:2048
	s_add_u32 s22, s22, 0x1000
	s_addc_u32 s23, s23, 0
	global_load_dword v28, v7, s[22:23]
	global_load_dword v29, v7, s[22:23] offset:2048
	s_add_u32 s22, s22, 0x1000
	s_addc_u32 s23, s23, 0
	global_load_dword v30, v7, s[22:23]
	global_load_dword v31, v7, s[22:23] offset:2048
	s_waitcnt vmcnt(8)
	v_mul_f32_e32 v43, 0xbfb8aa3b, v16
	v_mul_f32_e32 v44, 0xbfb8aa3b, v17
	v_mul_f32_e32 v45, 0xbfb8aa3b, v18
	v_mul_f32_e32 v46, 0xbfb8aa3b, v19
	v_mul_f32_e32 v47, 0xbfb8aa3b, v20
	v_mul_f32_e32 v48, 0xbfb8aa3b, v21
	v_mul_f32_e32 v49, 0xbfb8aa3b, v22
	v_mul_f32_e32 v50, 0xbfb8aa3b, v23
	v_exp_f32_e32 v43, v43
	v_exp_f32_e32 v44, v44
	v_exp_f32_e32 v45, v45
	v_exp_f32_e32 v46, v46
	v_exp_f32_e32 v47, v47
	v_exp_f32_e32 v48, v48
	v_exp_f32_e32 v49, v49
	v_exp_f32_e32 v50, v50
	v_add_f32_e32 v43, 1.0, v43
	v_add_f32_e32 v44, 1.0, v44
	v_add_f32_e32 v45, 1.0, v45
	v_add_f32_e32 v46, 1.0, v46
	v_add_f32_e32 v47, 1.0, v47
	v_add_f32_e32 v48, 1.0, v48
	v_add_f32_e32 v49, 1.0, v49
	v_add_f32_e32 v50, 1.0, v50
	v_rcp_f32_e32 v43, v43
	v_rcp_f32_e32 v44, v44
	v_rcp_f32_e32 v45, v45
	v_rcp_f32_e32 v46, v46
	v_rcp_f32_e32 v47, v47
	v_rcp_f32_e32 v48, v48
	v_rcp_f32_e32 v49, v49
	v_rcp_f32_e32 v50, v50
	v_mul_f32_e32 v16, v16, v43
	v_mul_f32_e32 v17, v17, v44
	v_mul_f32_e32 v18, v18, v45
	v_mul_f32_e32 v19, v19, v46
	v_mul_f32_e32 v20, v20, v47
	v_mul_f32_e32 v21, v21, v48
	v_mul_f32_e32 v22, v22, v49
	v_mul_f32_e32 v23, v23, v50
	ds_write_b32 v7, v16 offset:32768
	ds_write_b32 v7, v17 offset:34816
	ds_write_b32 v7, v18 offset:36864
	ds_write_b32 v7, v19 offset:38912
	ds_write_b32 v7, v20 offset:40960
	ds_write_b32 v7, v21 offset:43008
	ds_write_b32 v7, v22 offset:45056
	ds_write_b32 v7, v23 offset:47104
	s_add_u32 s22, s22, 0x1000
	s_addc_u32 s23, s23, 0
	global_load_dword v16, v7, s[22:23]
	global_load_dword v17, v7, s[22:23] offset:2048
	s_add_u32 s22, s22, 0x1000
	s_addc_u32 s23, s23, 0
	global_load_dword v18, v7, s[22:23]
	global_load_dword v19, v7, s[22:23] offset:2048
	s_add_u32 s22, s22, 0x1000
	s_addc_u32 s23, s23, 0
	global_load_dword v20, v7, s[22:23]
	global_load_dword v21, v7, s[22:23] offset:2048
	s_add_u32 s22, s22, 0x1000
	s_addc_u32 s23, s23, 0
	global_load_dword v22, v7, s[22:23]
	global_load_dword v23, v7, s[22:23] offset:2048
	s_waitcnt vmcnt(8)
	v_mul_f32_e32 v43, 0xbfb8aa3b, v24
	v_mul_f32_e32 v44, 0xbfb8aa3b, v25
	v_mul_f32_e32 v45, 0xbfb8aa3b, v26
	v_mul_f32_e32 v46, 0xbfb8aa3b, v27
	v_mul_f32_e32 v47, 0xbfb8aa3b, v28
	v_mul_f32_e32 v48, 0xbfb8aa3b, v29
	v_mul_f32_e32 v49, 0xbfb8aa3b, v30
	v_mul_f32_e32 v50, 0xbfb8aa3b, v31
	v_exp_f32_e32 v43, v43
	v_exp_f32_e32 v44, v44
	v_exp_f32_e32 v45, v45
	v_exp_f32_e32 v46, v46
	v_exp_f32_e32 v47, v47
	v_exp_f32_e32 v48, v48
	v_exp_f32_e32 v49, v49
	v_exp_f32_e32 v50, v50
	v_add_f32_e32 v43, 1.0, v43
	v_add_f32_e32 v44, 1.0, v44
	v_add_f32_e32 v45, 1.0, v45
	v_add_f32_e32 v46, 1.0, v46
	v_add_f32_e32 v47, 1.0, v47
	v_add_f32_e32 v48, 1.0, v48
	v_add_f32_e32 v49, 1.0, v49
	v_add_f32_e32 v50, 1.0, v50
	v_rcp_f32_e32 v43, v43
	v_rcp_f32_e32 v44, v44
	v_rcp_f32_e32 v45, v45
	v_rcp_f32_e32 v46, v46
	v_rcp_f32_e32 v47, v47
	v_rcp_f32_e32 v48, v48
	v_rcp_f32_e32 v49, v49
	v_rcp_f32_e32 v50, v50
	v_mul_f32_e32 v24, v24, v43
	v_mul_f32_e32 v25, v25, v44
	v_mul_f32_e32 v26, v26, v45
	v_mul_f32_e32 v27, v27, v46
	v_mul_f32_e32 v28, v28, v47
	v_mul_f32_e32 v29, v29, v48
	v_mul_f32_e32 v30, v30, v49
	v_mul_f32_e32 v31, v31, v50
	ds_write_b32 v7, v24 offset:49152
	ds_write_b32 v7, v25 offset:51200
	ds_write_b32 v7, v26 offset:53248
	ds_write_b32 v7, v27 offset:55296
	ds_write_b32 v7, v28 offset:57344
	ds_write_b32 v7, v29 offset:59392
	ds_write_b32 v7, v30 offset:61440
	ds_write_b32 v7, v31 offset:63488
	s_waitcnt vmcnt(0)
	v_mul_f32_e32 v43, 0xbfb8aa3b, v16
	v_mul_f32_e32 v44, 0xbfb8aa3b, v17
	v_mul_f32_e32 v45, 0xbfb8aa3b, v18
	v_mul_f32_e32 v46, 0xbfb8aa3b, v19
	v_mul_f32_e32 v47, 0xbfb8aa3b, v20
	v_mul_f32_e32 v48, 0xbfb8aa3b, v21
	v_mul_f32_e32 v49, 0xbfb8aa3b, v22
	v_mul_f32_e32 v50, 0xbfb8aa3b, v23
	v_exp_f32_e32 v43, v43
	v_exp_f32_e32 v44, v44
	v_exp_f32_e32 v45, v45
	v_exp_f32_e32 v46, v46
	v_exp_f32_e32 v47, v47
	v_exp_f32_e32 v48, v48
	v_exp_f32_e32 v49, v49
	v_exp_f32_e32 v50, v50
	v_add_f32_e32 v43, 1.0, v43
	v_add_f32_e32 v44, 1.0, v44
	v_add_f32_e32 v45, 1.0, v45
	v_add_f32_e32 v46, 1.0, v46
	v_add_f32_e32 v47, 1.0, v47
	v_add_f32_e32 v48, 1.0, v48
	v_add_f32_e32 v49, 1.0, v49
	v_add_f32_e32 v50, 1.0, v50
	v_rcp_f32_e32 v43, v43
	v_rcp_f32_e32 v44, v44
	v_rcp_f32_e32 v45, v45
	v_rcp_f32_e32 v46, v46
	v_rcp_f32_e32 v47, v47
	v_rcp_f32_e32 v48, v48
	v_rcp_f32_e32 v49, v49
	v_rcp_f32_e32 v50, v50
	v_mul_f32_e32 v16, v16, v43
	v_mul_f32_e32 v17, v17, v44
	v_mul_f32_e32 v18, v18, v45
	v_mul_f32_e32 v19, v19, v46
	v_mul_f32_e32 v20, v20, v47
	v_mul_f32_e32 v21, v21, v48
	v_mul_f32_e32 v22, v22, v49
	v_mul_f32_e32 v23, v23, v50
	ds_write_b32 v51, v16
	ds_write_b32 v51, v17 offset:2048
	ds_write_b32 v51, v18 offset:4096
	ds_write_b32 v51, v19 offset:6144
	ds_write_b32 v51, v20 offset:8192
	ds_write_b32 v51, v21 offset:10240
	ds_write_b32 v51, v22 offset:12288
	ds_write_b32 v51, v23 offset:14336
